# seams: L1 invalidate issued at arrival (overlaps the wait for the other workgroups) instead of after the release
# speedup vs baseline: 1.0616x; 1.0045x over previous
; __device__ __forceinline__ unsigned xb_ld(unsigned* p)              { return __hip_atomic_load(p, __ATOMIC_RELAXED, __HIP_MEMORY_SCOPE_AGENT); }
; __device__ __forceinline__ void xcd_barrier_complete(unsigned* bar, unsigned x, unsigned& nloc, unsigned& nx) {
;     const unsigned G = gridDim.x * gridDim.y * gridDim.z;
;     unsigned sum, cnt, mine, sp = 0u;
;     for (;;) {
;         sum = 0u; cnt = 0u; mine = 0u;
; #pragma unroll
;         for (unsigned j = 0; j < 16; ++j) { const unsigned c = xb_ld(&bar[XB_XCNT(j)]); sum += c; cnt += (c > 0u) ? 1u : 0u; mine = (j == x) ? c : mine; }
;         if (sum == G) break;
;         __builtin_amdgcn_s_sleep(1);
;         if ((++sp & 255u) == 0u) { if (xb_ld(&bar[XB_TMO])) break; if (sp > XB_SPIN_CAP) { atomicAdd(&bar[XB_TMO], 1u); break; } }
;     }
;     nloc = mine > 0u ? mine : 1u; nx = cnt > 0u ? cnt : 1u;
; }
; __device__ __forceinline__ void xcd_barrier(const XcdBarrier& b) {
;     asm volatile("s_waitcnt vmcnt(0)" ::: "memory");
;     __syncthreads();
;     if (threadIdx.x == 0) {
;         unsigned* bar = b.bar;
;         __builtin_amdgcn_s_waitcnt(0);
;         unsigned nloc = b.st[0], nx = b.st[1];
;         if (nloc == 0u) { xcd_barrier_complete(bar, b.x, nloc, nx); b.st[0] = nloc; b.st[1] = nx; }
.LBB0_140:
	s_cmp_gt_i32 s31, 1
	s_cselect_b64 s[0:1], -1, 0
	s_and_b64 s[4:5], s[8:9], s[0:1]
	s_andn2_b64 vcc, exec, s[4:5]
	s_cbranch_vccnz .LBB0_196
	s_waitcnt vmcnt(0)
	s_waitcnt lgkmcnt(0)
	s_barrier
	s_mov_b64 s[4:5], exec
	v_readlane_b32 s6, v249, 0
	v_readlane_b32 s7, v249, 1
	s_and_b64 s[6:7], s[4:5], s[6:7]
	s_mov_b64 exec, s[6:7]
	s_cbranch_execz .LBB0_195
	buffer_inv sc1
	s_add_i32 s3, 0, 0x23fc0
	v_mov_b32_e32 v0, s3
	s_waitcnt vmcnt(0) expcnt(0) lgkmcnt(0)
	ds_read_b32 v2, v0
	s_add_i32 s3, 0, 0x23fc4
	v_mov_b32_e32 v0, s3
	ds_read_b32 v0, v0
	s_waitcnt lgkmcnt(1)
	v_cmp_ne_u32_e32 vcc, 0, v2
	s_cbranch_vccnz .LBB0_157
	s_add_u32 s6, s28, 0x180200
	s_addc_u32 s7, s29, 0
	s_add_u32 s8, s28, 0x180400
	s_addc_u32 s9, s29, 0
	s_add_u32 s10, s28, 0x180500
	s_addc_u32 s11, s29, 0
	s_add_u32 s12, s28, 0x180600
	s_addc_u32 s13, s29, 0
	s_add_u32 s14, s28, 0x180700
	s_addc_u32 s15, s29, 0
	s_add_u32 s16, s28, 0x180800
	s_addc_u32 s17, s29, 0
	s_add_u32 s18, s28, 0x180900
	s_addc_u32 s19, s29, 0
	s_add_u32 s20, s28, 0x180a00
	s_addc_u32 s21, s29, 0
	s_add_u32 s34, s28, 0x180b00
	s_addc_u32 s35, s29, 0
	s_add_u32 s36, s28, 0x180c00
	s_addc_u32 s37, s29, 0
	s_add_u32 s40, s28, 0x180d00
	s_addc_u32 s41, s29, 0
	s_add_u32 s42, s28, 0x180e00
	s_addc_u32 s43, s29, 0
	s_add_u32 s46, s28, 0x180f00
	s_addc_u32 s47, s29, 0
	s_add_u32 s48, s28, 0x181000
	s_addc_u32 s49, s29, 0
	s_add_u32 s50, s28, 0x181100
	s_addc_u32 s51, s29, 0
	s_add_u32 s52, s28, 0x181200
	s_addc_u32 s53, s29, 0
	s_mul_i32 s3, s23, s96
	s_add_u32 s54, s28, 0x181300
	s_mul_i32 s3, s3, s22
	s_addc_u32 s55, s29, 0
	s_mov_b32 s62, 1
	v_mov_b32_e32 v16, 0
	s_branch .LBB0_145

; __device__ __forceinline__ unsigned xb_ld(unsigned* p)              { return __hip_atomic_load(p, __ATOMIC_RELAXED, __HIP_MEMORY_SCOPE_AGENT); }
; #define XB_SPIN(cond, bar) do { unsigned _sp = 0; while (cond) { __builtin_amdgcn_s_sleep(1); \
;     if ((++_sp & 255u) == 0u) { if (xb_ld(&(bar)[XB_TMO])) break; if (_sp > XB_SPIN_CAP) { atomicAdd(&(bar)[XB_TMO], 1u); break; } } } } while (0)
; __device__ __forceinline__ void xcd_barrier(const XcdBarrier& b) {
;     ...
;         } else {
;             XB_SPIN(xb_ld(&bar[XB_XGEN(b.x)]) == gen, bar);
;             __builtin_amdgcn_fence(__ATOMIC_ACQUIRE, "agent");
;             asm volatile("s_waitcnt vmcnt(0)" ::: "memory");
;         }
.LBB0_172:
	s_or_b64 exec, exec, s[10:11]
	s_waitcnt vmcnt(0)
	s_waitcnt vmcnt(0)

; __device__ __forceinline__ unsigned xb_ld(unsigned* p)              { return __hip_atomic_load(p, __ATOMIC_RELAXED, __HIP_MEMORY_SCOPE_AGENT); }
; __device__ __forceinline__ unsigned xb_add(unsigned* p, unsigned v) { return __hip_atomic_fetch_add(p, v, __ATOMIC_RELAXED, __HIP_MEMORY_SCOPE_AGENT); }
; #define XB_SPIN(cond, bar) do { unsigned _sp = 0; while (cond) { __builtin_amdgcn_s_sleep(1); \
;     if ((++_sp & 255u) == 0u) { if (xb_ld(&(bar)[XB_TMO])) break; if (_sp > XB_SPIN_CAP) { atomicAdd(&(bar)[XB_TMO], 1u); break; } } } } while (0)
; __device__ __forceinline__ void xcd_barrier(const XcdBarrier& b) {
;     ...
;             else XB_SPIN(xb_ld(&bar[XB_TOPGEN]) == tg, bar);
;             __builtin_amdgcn_fence(__ATOMIC_ACQUIRE, "agent");
;             xb_add(&bar[XB_XGEN(b.x)], 1u);
;             asm volatile("s_waitcnt vmcnt(0)" ::: "memory");
.LBB0_192:
	s_or_b64 exec, exec, s[8:9]
	s_mov_b64 s[8:9], exec
	v_mbcnt_lo_u32_b32 v0, s8, 0
	v_mbcnt_hi_u32_b32 v0, s9, v0
	v_cmp_eq_u32_e32 vcc, 0, v0
	s_waitcnt vmcnt(0)
	s_and_saveexec_b64 s[10:11], vcc
	s_cbranch_execz .LBB0_194
	s_bcnt1_i32_b64 s3, s[8:9]
	v_mov_b32_e32 v0, 0x2000
	v_mov_b32_e32 v1, s3
	global_atomic_add v0, v1, s[6:7] offset:1024

; __device__ __forceinline__ void xcd_barrier(const XcdBarrier& b) {
;     asm volatile("s_waitcnt vmcnt(0)" ::: "memory");
;     __syncthreads();
;     if (threadIdx.x == 0) {
;         unsigned* bar = b.bar;
;         __builtin_amdgcn_s_waitcnt(0);
;         unsigned nloc = b.st[0], nx = b.st[1];
;         if (nloc == 0u) { xcd_barrier_complete(bar, b.x, nloc, nx); b.st[0] = nloc; b.st[1] = nx; }
.LBB0_231:
	s_cmp_gt_i32 s31, 2
	s_cselect_b64 s[0:1], -1, 0
	s_and_b64 s[4:5], s[6:7], s[0:1]
	s_andn2_b64 vcc, exec, s[4:5]
	s_cbranch_vccnz .LBB0_285
	s_waitcnt vmcnt(0)
	s_waitcnt vmcnt(0) lgkmcnt(0)
	s_barrier
	s_mov_b64 s[4:5], exec
	v_readlane_b32 s6, v249, 0
	v_readlane_b32 s7, v249, 1
	s_and_b64 s[6:7], s[4:5], s[6:7]
	s_mov_b64 exec, s[6:7]
	s_cbranch_execz .LBB0_284
	buffer_inv sc1
	s_add_i32 s3, 0, 0x23fc0
	v_mov_b32_e32 v0, s3
	s_waitcnt vmcnt(0) expcnt(0) lgkmcnt(0)
	ds_read_b32 v2, v0
	s_add_i32 s3, 0, 0x23fc4
	v_mov_b32_e32 v0, s3
	ds_read_b32 v0, v0
	s_waitcnt lgkmcnt(1)
	v_cmp_ne_u32_e32 vcc, 0, v2
	s_cbranch_vccnz .LBB0_248
	s_add_u32 s6, s28, 0x180200
	s_addc_u32 s7, s29, 0
	s_add_u32 s8, s28, 0x180400
	s_addc_u32 s9, s29, 0
	s_add_u32 s10, s28, 0x180500
	s_addc_u32 s11, s29, 0
	s_add_u32 s12, s28, 0x180600
	s_addc_u32 s13, s29, 0
	s_add_u32 s14, s28, 0x180700
	s_addc_u32 s15, s29, 0
	s_add_u32 s16, s28, 0x180800
	s_addc_u32 s17, s29, 0
	s_add_u32 s18, s28, 0x180900
	s_addc_u32 s19, s29, 0
	s_add_u32 s20, s28, 0x180a00
	s_addc_u32 s21, s29, 0
	s_add_u32 s34, s28, 0x180b00
	s_addc_u32 s35, s29, 0
	s_add_u32 s42, s28, 0x180c00
	s_addc_u32 s43, s29, 0
	s_add_u32 s46, s28, 0x180d00
	s_addc_u32 s47, s29, 0
	s_add_u32 s48, s28, 0x180e00
	s_addc_u32 s49, s29, 0
	s_add_u32 s50, s28, 0x180f00
	s_addc_u32 s51, s29, 0
	s_add_u32 s52, s28, 0x181000
	s_addc_u32 s53, s29, 0
	s_add_u32 s54, s28, 0x181100
	s_addc_u32 s55, s29, 0
	s_add_u32 s56, s28, 0x181200
	s_addc_u32 s57, s29, 0
	s_mul_i32 s3, s23, s96
	s_add_u32 s58, s28, 0x181300
	s_mul_i32 s3, s3, s22
	s_addc_u32 s59, s29, 0
	s_mov_b32 s66, 1
	v_mov_b32_e32 v16, 0
	s_branch .LBB0_236

; __device__ __forceinline__ void xcd_barrier(const XcdBarrier& b) {
;     asm volatile("s_waitcnt vmcnt(0)" ::: "memory");
;     __syncthreads();
;     if (threadIdx.x == 0) {
;         unsigned* bar = b.bar;
;         __builtin_amdgcn_s_waitcnt(0);
;         unsigned nloc = b.st[0], nx = b.st[1];
;         if (nloc == 0u) { xcd_barrier_complete(bar, b.x, nloc, nx); b.st[0] = nloc; b.st[1] = nx; }
.LBB0_332:
	s_cmp_gt_i32 s31, 3
	s_cselect_b64 s[0:1], -1, 0
	s_and_b64 s[4:5], s[8:9], s[0:1]
	s_andn2_b64 vcc, exec, s[4:5]
	s_cbranch_vccnz .LBB0_386
	s_waitcnt vmcnt(0)
	s_waitcnt vmcnt(0) lgkmcnt(0)
	s_barrier
	s_mov_b64 s[4:5], exec
	v_readlane_b32 s6, v249, 0
	v_readlane_b32 s7, v249, 1
	s_and_b64 s[6:7], s[4:5], s[6:7]
	s_mov_b64 exec, s[6:7]
	s_cbranch_execz .LBB0_385
	buffer_inv sc1
	s_add_i32 s3, 0, 0x23fc0
	v_mov_b32_e32 v0, s3
	s_waitcnt vmcnt(0) expcnt(0) lgkmcnt(0)
	ds_read_b32 v2, v0
	s_add_i32 s3, 0, 0x23fc4
	v_mov_b32_e32 v0, s3
	ds_read_b32 v0, v0
	s_waitcnt lgkmcnt(1)
	v_cmp_ne_u32_e32 vcc, 0, v2
	s_cbranch_vccnz .LBB0_349
	s_add_u32 s6, s28, 0x180200
	s_addc_u32 s7, s29, 0
	s_add_u32 s8, s28, 0x180400
	s_addc_u32 s9, s29, 0
	s_add_u32 s10, s28, 0x180500
	s_addc_u32 s11, s29, 0
	s_add_u32 s12, s28, 0x180600
	s_addc_u32 s13, s29, 0
	s_add_u32 s14, s28, 0x180700
	s_addc_u32 s15, s29, 0
	s_add_u32 s16, s28, 0x180800
	s_addc_u32 s17, s29, 0
	s_add_u32 s18, s28, 0x180900
	s_addc_u32 s19, s29, 0
	s_add_u32 s20, s28, 0x180a00
	s_addc_u32 s21, s29, 0
	s_add_u32 s34, s28, 0x180b00
	s_addc_u32 s35, s29, 0
	s_add_u32 s42, s28, 0x180c00
	s_addc_u32 s43, s29, 0
	s_add_u32 s46, s28, 0x180d00
	s_addc_u32 s47, s29, 0
	s_add_u32 s48, s28, 0x180e00
	s_addc_u32 s49, s29, 0
	s_add_u32 s50, s28, 0x180f00
	s_addc_u32 s51, s29, 0
	s_add_u32 s52, s28, 0x181000
	s_addc_u32 s53, s29, 0
	s_add_u32 s54, s28, 0x181100
	s_addc_u32 s55, s29, 0
	s_add_u32 s56, s28, 0x181200
	s_addc_u32 s57, s29, 0
	s_mul_i32 s3, s23, s96
	s_add_u32 s58, s28, 0x181300
	s_mul_i32 s3, s3, s22
	s_addc_u32 s59, s29, 0
	s_mov_b32 s66, 1
	v_mov_b32_e32 v16, 0
	s_branch .LBB0_337

; __device__ __forceinline__ void xcd_barrier(const XcdBarrier& b) {
;     asm volatile("s_waitcnt vmcnt(0)" ::: "memory");
;     __syncthreads();
;     if (threadIdx.x == 0) {
;         unsigned* bar = b.bar;
;         __builtin_amdgcn_s_waitcnt(0);
;         unsigned nloc = b.st[0], nx = b.st[1];
;         if (nloc == 0u) { xcd_barrier_complete(bar, b.x, nloc, nx); b.st[0] = nloc; b.st[1] = nx; }
.LBB0_425:
	s_cmp_gt_i32 s31, 4
	s_cselect_b64 s[0:1], -1, 0
	s_and_b64 s[4:5], s[6:7], s[0:1]
	s_andn2_b64 vcc, exec, s[4:5]
	s_cbranch_vccnz .LBB0_479
	s_waitcnt vmcnt(0)
	s_waitcnt vmcnt(0) lgkmcnt(0)
	s_barrier
	s_mov_b64 s[4:5], exec
	v_readlane_b32 s6, v249, 0
	v_readlane_b32 s7, v249, 1
	s_and_b64 s[6:7], s[4:5], s[6:7]
	s_mov_b64 exec, s[6:7]
	s_cbranch_execz .LBB0_478
	buffer_inv sc1
	s_add_i32 s3, 0, 0x23fc0
	v_mov_b32_e32 v0, s3
	s_waitcnt vmcnt(0) expcnt(0) lgkmcnt(0)
	ds_read_b32 v2, v0
	s_add_i32 s3, 0, 0x23fc4
	v_mov_b32_e32 v0, s3
	ds_read_b32 v0, v0
	s_waitcnt lgkmcnt(1)
	v_cmp_ne_u32_e32 vcc, 0, v2
	s_cbranch_vccnz .LBB0_442
	s_add_u32 s6, s28, 0x180200
	s_addc_u32 s7, s29, 0
	s_add_u32 s8, s28, 0x180400
	s_addc_u32 s9, s29, 0
	s_add_u32 s10, s28, 0x180500
	s_addc_u32 s11, s29, 0
	s_add_u32 s12, s28, 0x180600
	s_addc_u32 s13, s29, 0
	s_add_u32 s14, s28, 0x180700
	s_addc_u32 s15, s29, 0
	s_add_u32 s16, s28, 0x180800
	s_addc_u32 s17, s29, 0
	s_add_u32 s18, s28, 0x180900
	s_addc_u32 s19, s29, 0
	s_add_u32 s20, s28, 0x180a00
	s_addc_u32 s21, s29, 0
	s_add_u32 s34, s28, 0x180b00
	s_addc_u32 s35, s29, 0
	s_add_u32 s42, s28, 0x180c00
	s_addc_u32 s43, s29, 0
	s_add_u32 s48, s28, 0x180d00
	s_addc_u32 s49, s29, 0
	s_add_u32 s50, s28, 0x180e00
	s_addc_u32 s51, s29, 0
	s_add_u32 s52, s28, 0x180f00
	s_addc_u32 s53, s29, 0
	s_add_u32 s54, s28, 0x181000
	s_addc_u32 s55, s29, 0
	s_add_u32 s56, s28, 0x181100
	s_addc_u32 s57, s29, 0
	s_add_u32 s58, s28, 0x181200
	s_addc_u32 s59, s29, 0
	s_mul_i32 s3, s23, s96
	s_add_u32 s60, s28, 0x181300
	s_mul_i32 s3, s3, s22
	s_addc_u32 s61, s29, 0
	s_mov_b32 s68, 1
	v_mov_b32_e32 v16, 0
	s_branch .LBB0_430

; __device__ __forceinline__ void xcd_barrier(const XcdBarrier& b) {
;     asm volatile("s_waitcnt vmcnt(0)" ::: "memory");
;     __syncthreads();
;     if (threadIdx.x == 0) {
;         unsigned* bar = b.bar;
;         __builtin_amdgcn_s_waitcnt(0);
;         unsigned nloc = b.st[0], nx = b.st[1];
;         if (nloc == 0u) { xcd_barrier_complete(bar, b.x, nloc, nx); b.st[0] = nloc; b.st[1] = nx; }
.LBB0_490:
	s_cmp_gt_i32 s31, 5
	s_cselect_b64 s[4:5], -1, 0
	s_and_b64 s[0:1], s[8:9], s[4:5]
	v_readlane_b32 s80, v249, 0
	s_andn2_b64 vcc, exec, s[0:1]
	v_readlane_b32 s81, v249, 1
	s_cbranch_vccnz .LBB0_544
	s_waitcnt vmcnt(0)
	s_waitcnt vmcnt(0) lgkmcnt(0)
	s_barrier
	s_and_saveexec_b64 s[0:1], s[80:81]
	s_cbranch_execz .LBB0_543
	buffer_inv sc1
	s_add_i32 s3, 0, 0x23fc0
	v_mov_b32_e32 v0, s3
	s_waitcnt vmcnt(0) expcnt(0) lgkmcnt(0)
	ds_read_b32 v2, v0
	s_add_i32 s3, 0, 0x23fc4
	v_mov_b32_e32 v0, s3
	ds_read_b32 v0, v0
	s_waitcnt lgkmcnt(1)
	v_cmp_ne_u32_e32 vcc, 0, v2
	s_cbranch_vccnz .LBB0_507
	s_add_u32 s8, s28, 0x180200
	s_addc_u32 s9, s29, 0
	s_add_u32 s10, s28, 0x180400
	s_addc_u32 s11, s29, 0
	s_add_u32 s12, s28, 0x180500
	s_addc_u32 s13, s29, 0
	s_add_u32 s14, s28, 0x180600
	s_addc_u32 s15, s29, 0
	s_add_u32 s16, s28, 0x180700
	s_addc_u32 s17, s29, 0
	s_add_u32 s18, s28, 0x180800
	s_addc_u32 s19, s29, 0
	s_add_u32 s20, s28, 0x180900
	s_addc_u32 s21, s29, 0
	s_add_u32 s34, s28, 0x180a00
	s_addc_u32 s35, s29, 0
	s_add_u32 s48, s28, 0x180b00
	s_addc_u32 s49, s29, 0
	s_add_u32 s50, s28, 0x180c00
	s_addc_u32 s51, s29, 0
	s_add_u32 s52, s28, 0x180d00
	s_addc_u32 s53, s29, 0
	s_add_u32 s54, s28, 0x180e00
	s_addc_u32 s55, s29, 0
	s_add_u32 s56, s28, 0x180f00
	s_addc_u32 s57, s29, 0
	s_add_u32 s58, s28, 0x181000
	s_addc_u32 s59, s29, 0
	s_add_u32 s60, s28, 0x181100
	s_addc_u32 s61, s29, 0
	s_add_u32 s62, s28, 0x181200
	s_addc_u32 s63, s29, 0
	s_mul_i32 s3, s23, s96
	s_add_u32 s64, s28, 0x181300
	s_mul_i32 s3, s3, s22
	s_addc_u32 s65, s29, 0
	s_mov_b32 s72, 1
	v_mov_b32_e32 v16, 0
	s_branch .LBB0_495

; __device__ __forceinline__ unsigned xb_ld(unsigned* p)              { return __hip_atomic_load(p, __ATOMIC_RELAXED, __HIP_MEMORY_SCOPE_AGENT); }
; #define XB_SPIN(cond, bar) do { unsigned _sp = 0; while (cond) { __builtin_amdgcn_s_sleep(1); \
;     if ((++_sp & 255u) == 0u) { if (xb_ld(&(bar)[XB_TMO])) break; if (_sp > XB_SPIN_CAP) { atomicAdd(&(bar)[XB_TMO], 1u); break; } } } } while (0)
; __device__ __forceinline__ void xcd_barrier(const XcdBarrier& b) {
;     ...
;         } else {
;             XB_SPIN(xb_ld(&bar[XB_XGEN(b.x)]) == gen, bar);
;             __builtin_amdgcn_fence(__ATOMIC_ACQUIRE, "agent");
;             asm volatile("s_waitcnt vmcnt(0)" ::: "memory");
;         }
.LBB0_522:
	s_or_b64 exec, exec, s[12:13]
	s_waitcnt vmcnt(0)
	s_waitcnt vmcnt(0)

; __device__ __forceinline__ unsigned xb_ld(unsigned* p)              { return __hip_atomic_load(p, __ATOMIC_RELAXED, __HIP_MEMORY_SCOPE_AGENT); }
; __device__ __forceinline__ unsigned xb_add(unsigned* p, unsigned v) { return __hip_atomic_fetch_add(p, v, __ATOMIC_RELAXED, __HIP_MEMORY_SCOPE_AGENT); }
; #define XB_SPIN(cond, bar) do { unsigned _sp = 0; while (cond) { __builtin_amdgcn_s_sleep(1); \
;     if ((++_sp & 255u) == 0u) { if (xb_ld(&(bar)[XB_TMO])) break; if (_sp > XB_SPIN_CAP) { atomicAdd(&(bar)[XB_TMO], 1u); break; } } } } while (0)
; __device__ __forceinline__ void xcd_barrier(const XcdBarrier& b) {
;     ...
;             else XB_SPIN(xb_ld(&bar[XB_TOPGEN]) == tg, bar);
;             __builtin_amdgcn_fence(__ATOMIC_ACQUIRE, "agent");
;             xb_add(&bar[XB_XGEN(b.x)], 1u);
;             asm volatile("s_waitcnt vmcnt(0)" ::: "memory");
.LBB0_540:
	s_or_b64 exec, exec, s[10:11]
	s_mov_b64 s[10:11], exec
	v_mbcnt_lo_u32_b32 v0, s10, 0
	v_mbcnt_hi_u32_b32 v0, s11, v0
	v_cmp_eq_u32_e32 vcc, 0, v0
	s_waitcnt vmcnt(0)
	s_and_saveexec_b64 s[12:13], vcc
	s_cbranch_execz .LBB0_542
	s_bcnt1_i32_b64 s3, s[10:11]
	v_mov_b32_e32 v0, 0x2000
	v_mov_b32_e32 v1, s3
	global_atomic_add v0, v1, s[8:9] offset:1024

; __device__ __forceinline__ void xcd_barrier(const XcdBarrier& b) {
;     asm volatile("s_waitcnt vmcnt(0)" ::: "memory");
;     __syncthreads();
;     if (threadIdx.x == 0) {
;         unsigned* bar = b.bar;
;         __builtin_amdgcn_s_waitcnt(0);
;         unsigned nloc = b.st[0], nx = b.st[1];
;         if (nloc == 0u) { xcd_barrier_complete(bar, b.x, nloc, nx); b.st[0] = nloc; b.st[1] = nx; }
.LBB0_552:
	s_cmp_gt_i32 s31, 6
	s_cselect_b64 s[4:5], -1, 0
	s_and_b64 s[6:7], s[48:49], s[4:5]
	s_andn2_b64 vcc, exec, s[6:7]
	s_cbranch_vccnz .LBB0_606
	s_waitcnt vmcnt(0)
	s_waitcnt vmcnt(0) lgkmcnt(0)
	s_barrier
	s_and_saveexec_b64 s[6:7], s[80:81]
	s_cbranch_execz .LBB0_605
	buffer_inv sc1
	s_add_i32 s3, 0, 0x23fc0
	v_mov_b32_e32 v0, s3
	s_waitcnt vmcnt(0) expcnt(0) lgkmcnt(0)
	ds_read_b32 v2, v0
	s_add_i32 s3, 0, 0x23fc4
	v_mov_b32_e32 v0, s3
	ds_read_b32 v0, v0
	s_waitcnt lgkmcnt(1)
	v_cmp_ne_u32_e32 vcc, 0, v2
	s_cbranch_vccnz .LBB0_569
	s_add_u32 s8, s28, 0x180200
	s_addc_u32 s9, s29, 0
	s_add_u32 s10, s28, 0x180400
	s_addc_u32 s11, s29, 0
	s_add_u32 s12, s28, 0x180500
	s_addc_u32 s13, s29, 0
	s_add_u32 s14, s28, 0x180600
	s_addc_u32 s15, s29, 0
	s_add_u32 s16, s28, 0x180700
	s_addc_u32 s17, s29, 0
	s_add_u32 s18, s28, 0x180800
	s_addc_u32 s19, s29, 0
	s_add_u32 s20, s28, 0x180900
	s_addc_u32 s21, s29, 0
	s_add_u32 s34, s28, 0x180a00
	s_addc_u32 s35, s29, 0
	s_add_u32 s38, s28, 0x180b00
	s_addc_u32 s39, s29, 0
	s_add_u32 s46, s28, 0x180c00
	s_addc_u32 s47, s29, 0
	s_add_u32 s48, s28, 0x180d00
	s_addc_u32 s49, s29, 0
	s_add_u32 s50, s28, 0x180e00
	s_addc_u32 s51, s29, 0
	s_add_u32 s52, s28, 0x180f00
	s_addc_u32 s53, s29, 0
	s_add_u32 s54, s28, 0x181000
	s_addc_u32 s55, s29, 0
	s_add_u32 s56, s28, 0x181100
	s_addc_u32 s57, s29, 0
	s_add_u32 s58, s28, 0x181200
	s_addc_u32 s59, s29, 0
	s_mul_i32 s3, s23, s96
	s_add_u32 s60, s28, 0x181300
	s_mul_i32 s3, s3, s22
	s_addc_u32 s61, s29, 0
	s_mov_b32 s33, 1
	v_mov_b32_e32 v16, 0
	s_branch .LBB0_557

; __device__ __forceinline__ void xcd_barrier(const XcdBarrier& b) {
;     asm volatile("s_waitcnt vmcnt(0)" ::: "memory");
;     __syncthreads();
;     if (threadIdx.x == 0) {
;         unsigned* bar = b.bar;
;         __builtin_amdgcn_s_waitcnt(0);
;         unsigned nloc = b.st[0], nx = b.st[1];
;         if (nloc == 0u) { xcd_barrier_complete(bar, b.x, nloc, nx); b.st[0] = nloc; b.st[1] = nx; }
.LBB0_631:
	s_cmp_gt_i32 s31, 7
	s_cselect_b64 s[0:1], -1, 0
	s_and_b64 s[4:5], s[6:7], s[0:1]
	s_andn2_b64 vcc, exec, s[4:5]
	s_cbranch_vccnz .LBB0_685
	s_waitcnt vmcnt(0)
	s_waitcnt vmcnt(0) lgkmcnt(0)
	s_barrier
	s_and_saveexec_b64 s[4:5], s[80:81]
	s_cbranch_execz .LBB0_684
	buffer_inv sc1
	s_add_i32 s3, 0, 0x23fc0
	v_mov_b32_e32 v0, s3
	s_waitcnt vmcnt(0) expcnt(0) lgkmcnt(0)
	ds_read_b32 v2, v0
	s_add_i32 s3, 0, 0x23fc4
	v_mov_b32_e32 v0, s3
	ds_read_b32 v0, v0
	s_waitcnt lgkmcnt(1)
	v_cmp_ne_u32_e32 vcc, 0, v2
	s_cbranch_vccnz .LBB0_648
	s_add_u32 s6, s28, 0x180200
	s_addc_u32 s7, s29, 0
	s_add_u32 s8, s28, 0x180400
	s_addc_u32 s9, s29, 0
	s_add_u32 s10, s28, 0x180500
	s_addc_u32 s11, s29, 0
	s_add_u32 s12, s28, 0x180600
	s_addc_u32 s13, s29, 0
	s_add_u32 s14, s28, 0x180700
	s_addc_u32 s15, s29, 0
	s_add_u32 s16, s28, 0x180800
	s_addc_u32 s17, s29, 0
	s_add_u32 s18, s28, 0x180900
	s_addc_u32 s19, s29, 0
	s_add_u32 s20, s28, 0x180a00
	s_addc_u32 s21, s29, 0
	s_add_u32 s34, s28, 0x180b00
	s_addc_u32 s35, s29, 0
	s_add_u32 s38, s28, 0x180c00
	s_addc_u32 s39, s29, 0
	s_add_u32 s44, s28, 0x180d00
	s_addc_u32 s45, s29, 0
	s_add_u32 s46, s28, 0x180e00
	s_addc_u32 s47, s29, 0
	s_add_u32 s48, s28, 0x180f00
	s_addc_u32 s49, s29, 0
	s_add_u32 s50, s28, 0x181000
	s_addc_u32 s51, s29, 0
	s_add_u32 s52, s28, 0x181100
	s_addc_u32 s53, s29, 0
	s_add_u32 s54, s28, 0x181200
	s_addc_u32 s55, s29, 0
	s_mul_i32 s3, s23, s96
	s_add_u32 s56, s28, 0x181300
	s_mul_i32 s3, s3, s22
	s_addc_u32 s57, s29, 0
	s_mov_b32 s33, 1
	v_mov_b32_e32 v16, 0
	s_branch .LBB0_636

; __device__ __forceinline__ void xcd_barrier(const XcdBarrier& b) {
;     asm volatile("s_waitcnt vmcnt(0)" ::: "memory");
;     __syncthreads();
;     if (threadIdx.x == 0) {
;         unsigned* bar = b.bar;
;         __builtin_amdgcn_s_waitcnt(0);
;         unsigned nloc = b.st[0], nx = b.st[1];
;         if (nloc == 0u) { xcd_barrier_complete(bar, b.x, nloc, nx); b.st[0] = nloc; b.st[1] = nx; }
.LBB0_728:
	s_cmp_gt_i32 s31, 8
	s_cselect_b64 s[4:5], -1, 0
	s_and_b64 s[0:1], s[0:1], s[4:5]
	s_andn2_b64 vcc, exec, s[0:1]
	s_cbranch_vccnz .LBB0_782
	s_waitcnt vmcnt(0)
	s_waitcnt vmcnt(0) lgkmcnt(0)
	s_barrier
	s_and_saveexec_b64 s[0:1], s[80:81]
	s_cbranch_execz .LBB0_781
	buffer_inv sc1
	s_add_i32 s3, 0, 0x23fc0
	v_mov_b32_e32 v0, s3
	s_waitcnt vmcnt(0) expcnt(0) lgkmcnt(0)
	ds_read_b32 v2, v0
	s_add_i32 s3, 0, 0x23fc4
	v_mov_b32_e32 v0, s3
	ds_read_b32 v0, v0
	s_waitcnt lgkmcnt(1)
	v_cmp_ne_u32_e32 vcc, 0, v2
	s_cbranch_vccnz .LBB0_745
	s_add_u32 s6, s28, 0x180200
	s_addc_u32 s7, s29, 0
	s_add_u32 s8, s28, 0x180400
	s_addc_u32 s9, s29, 0
	s_add_u32 s10, s28, 0x180500
	s_addc_u32 s11, s29, 0
	s_add_u32 s12, s28, 0x180600
	s_addc_u32 s13, s29, 0
	s_add_u32 s14, s28, 0x180700
	s_addc_u32 s15, s29, 0
	s_add_u32 s16, s28, 0x180800
	s_addc_u32 s17, s29, 0
	s_add_u32 s18, s28, 0x180900
	s_addc_u32 s19, s29, 0
	s_add_u32 s20, s28, 0x180a00
	s_addc_u32 s21, s29, 0
	s_add_u32 s34, s28, 0x180b00
	s_addc_u32 s35, s29, 0
	s_add_u32 s38, s28, 0x180c00
	s_addc_u32 s39, s29, 0
	s_add_u32 s44, s28, 0x180d00
	s_addc_u32 s45, s29, 0
	s_add_u32 s46, s28, 0x180e00
	s_addc_u32 s47, s29, 0
	s_add_u32 s48, s28, 0x180f00
	s_addc_u32 s49, s29, 0
	s_add_u32 s50, s28, 0x181000
	s_addc_u32 s51, s29, 0
	s_add_u32 s52, s28, 0x181100
	s_addc_u32 s53, s29, 0
	s_add_u32 s54, s28, 0x181200
	s_addc_u32 s55, s29, 0
	s_mul_i32 s3, s23, s96
	s_add_u32 s56, s28, 0x181300
	s_mul_i32 s3, s3, s22
	s_addc_u32 s57, s29, 0
	s_mov_b32 s33, 1
	v_mov_b32_e32 v16, 0
	s_branch .LBB0_733

; __device__ __forceinline__ void xcd_barrier(const XcdBarrier& b) {
;     asm volatile("s_waitcnt vmcnt(0)" ::: "memory");
;     __syncthreads();
;     if (threadIdx.x == 0) {
;         unsigned* bar = b.bar;
;         __builtin_amdgcn_s_waitcnt(0);
;         unsigned nloc = b.st[0], nx = b.st[1];
;         if (nloc == 0u) { xcd_barrier_complete(bar, b.x, nloc, nx); b.st[0] = nloc; b.st[1] = nx; }
.LBB0_817:
	s_cmp_gt_i32 s31, 9
	s_cselect_b64 s[0:1], -1, 0
	s_and_b64 s[4:5], s[6:7], s[0:1]
	s_andn2_b64 vcc, exec, s[4:5]
	s_cbranch_vccnz .LBB0_871
	s_waitcnt vmcnt(0)
	s_waitcnt vmcnt(0) lgkmcnt(0)
	s_barrier
	s_and_saveexec_b64 s[4:5], s[80:81]
	s_cbranch_execz .LBB0_870
	buffer_inv sc1
	s_add_i32 s3, 0, 0x23fc0
	v_mov_b32_e32 v0, s3
	s_waitcnt vmcnt(0) expcnt(0) lgkmcnt(0)
	ds_read_b32 v2, v0
	s_add_i32 s3, 0, 0x23fc4
	v_mov_b32_e32 v0, s3
	ds_read_b32 v0, v0
	s_waitcnt lgkmcnt(1)
	v_cmp_ne_u32_e32 vcc, 0, v2
	s_cbranch_vccnz .LBB0_834
	s_add_u32 s6, s28, 0x180200
	s_addc_u32 s7, s29, 0
	s_add_u32 s8, s28, 0x180400
	s_addc_u32 s9, s29, 0
	s_add_u32 s10, s28, 0x180500
	s_addc_u32 s11, s29, 0
	s_add_u32 s12, s28, 0x180600
	s_addc_u32 s13, s29, 0
	s_add_u32 s14, s28, 0x180700
	s_addc_u32 s15, s29, 0
	s_add_u32 s16, s28, 0x180800
	s_addc_u32 s17, s29, 0
	s_add_u32 s18, s28, 0x180900
	s_addc_u32 s19, s29, 0
	s_add_u32 s20, s28, 0x180a00
	s_addc_u32 s21, s29, 0
	s_add_u32 s34, s28, 0x180b00
	s_addc_u32 s35, s29, 0
	s_add_u32 s38, s28, 0x180c00
	s_addc_u32 s39, s29, 0
	s_add_u32 s44, s28, 0x180d00
	s_addc_u32 s45, s29, 0
	s_add_u32 s46, s28, 0x180e00
	s_addc_u32 s47, s29, 0
	s_add_u32 s48, s28, 0x180f00
	s_addc_u32 s49, s29, 0
	s_add_u32 s50, s28, 0x181000
	s_addc_u32 s51, s29, 0
	s_add_u32 s52, s28, 0x181100
	s_addc_u32 s53, s29, 0
	s_add_u32 s54, s28, 0x181200
	s_addc_u32 s55, s29, 0
	s_mul_i32 s3, s23, s96
	s_add_u32 s56, s28, 0x181300
	s_mul_i32 s3, s3, s22
	s_addc_u32 s57, s29, 0
	s_mov_b32 s33, 1
	v_mov_b32_e32 v16, 0
	s_branch .LBB0_822

; __device__ __forceinline__ void xcd_barrier(const XcdBarrier& b) {
;     asm volatile("s_waitcnt vmcnt(0)" ::: "memory");
;     __syncthreads();
;     if (threadIdx.x == 0) {
;         unsigned* bar = b.bar;
;         __builtin_amdgcn_s_waitcnt(0);
;         unsigned nloc = b.st[0], nx = b.st[1];
;         if (nloc == 0u) { xcd_barrier_complete(bar, b.x, nloc, nx); b.st[0] = nloc; b.st[1] = nx; }
.LBB0_918:
	s_cmp_gt_i32 s31, 10
	s_cselect_b64 s[0:1], -1, 0
	s_and_b64 s[4:5], s[8:9], s[0:1]
	s_andn2_b64 vcc, exec, s[4:5]
	s_cbranch_vccnz .LBB0_972
	s_waitcnt vmcnt(0)
	s_waitcnt vmcnt(0) lgkmcnt(0)
	s_barrier
	s_and_saveexec_b64 s[4:5], s[80:81]
	s_cbranch_execz .LBB0_971
	buffer_inv sc1
	s_add_i32 s3, 0, 0x23fc0
	v_mov_b32_e32 v0, s3
	s_waitcnt vmcnt(0) expcnt(0) lgkmcnt(0)
	ds_read_b32 v2, v0
	s_add_i32 s3, 0, 0x23fc4
	v_mov_b32_e32 v0, s3
	ds_read_b32 v0, v0
	s_waitcnt lgkmcnt(1)
	v_cmp_ne_u32_e32 vcc, 0, v2
	s_cbranch_vccnz .LBB0_935
	s_add_u32 s6, s28, 0x180200
	s_addc_u32 s7, s29, 0
	s_add_u32 s8, s28, 0x180400
	s_addc_u32 s9, s29, 0
	s_add_u32 s10, s28, 0x180500
	s_addc_u32 s11, s29, 0
	s_add_u32 s12, s28, 0x180600
	s_addc_u32 s13, s29, 0
	s_add_u32 s14, s28, 0x180700
	s_addc_u32 s15, s29, 0
	s_add_u32 s16, s28, 0x180800
	s_addc_u32 s17, s29, 0
	s_add_u32 s18, s28, 0x180900
	s_addc_u32 s19, s29, 0
	s_add_u32 s20, s28, 0x180a00
	s_addc_u32 s21, s29, 0
	s_add_u32 s34, s28, 0x180b00
	s_addc_u32 s35, s29, 0
	s_add_u32 s38, s28, 0x180c00
	s_addc_u32 s39, s29, 0
	s_add_u32 s44, s28, 0x180d00
	s_addc_u32 s45, s29, 0
	s_add_u32 s46, s28, 0x180e00
	s_addc_u32 s47, s29, 0
	s_add_u32 s48, s28, 0x180f00
	s_addc_u32 s49, s29, 0
	s_add_u32 s50, s28, 0x181000
	s_addc_u32 s51, s29, 0
	s_add_u32 s52, s28, 0x181100
	s_addc_u32 s53, s29, 0
	s_add_u32 s54, s28, 0x181200
	s_addc_u32 s55, s29, 0
	s_mul_i32 s3, s23, s96
	s_add_u32 s56, s28, 0x181300
	s_mul_i32 s3, s3, s22
	s_addc_u32 s57, s29, 0
	s_mov_b32 s33, 1
	v_mov_b32_e32 v16, 0
	s_branch .LBB0_923

; __device__ __forceinline__ void xcd_barrier(const XcdBarrier& b) {
;     asm volatile("s_waitcnt vmcnt(0)" ::: "memory");
;     __syncthreads();
;     if (threadIdx.x == 0) {
;         unsigned* bar = b.bar;
;         __builtin_amdgcn_s_waitcnt(0);
;         unsigned nloc = b.st[0], nx = b.st[1];
;         if (nloc == 0u) { xcd_barrier_complete(bar, b.x, nloc, nx); b.st[0] = nloc; b.st[1] = nx; }
.LBB0_1007:
	s_cmp_gt_i32 s31, 11
	s_cselect_b64 s[0:1], -1, 0
	s_and_b64 s[4:5], s[6:7], s[0:1]
	s_andn2_b64 vcc, exec, s[4:5]
	s_cbranch_vccnz .LBB0_1061
	s_waitcnt vmcnt(0)
	s_waitcnt vmcnt(0) lgkmcnt(0)
	s_barrier
	s_and_saveexec_b64 s[4:5], s[80:81]
	s_cbranch_execz .LBB0_1060
	buffer_inv sc1
	s_add_i32 s3, 0, 0x23fc0
	v_mov_b32_e32 v0, s3
	s_waitcnt vmcnt(0) expcnt(0) lgkmcnt(0)
	ds_read_b32 v2, v0
	s_add_i32 s3, 0, 0x23fc4
	v_mov_b32_e32 v0, s3
	ds_read_b32 v0, v0
	s_waitcnt lgkmcnt(1)
	v_cmp_ne_u32_e32 vcc, 0, v2
	s_cbranch_vccnz .LBB0_1024
	s_add_u32 s6, s28, 0x180200
	s_addc_u32 s7, s29, 0
	s_add_u32 s8, s28, 0x180400
	s_addc_u32 s9, s29, 0
	s_add_u32 s10, s28, 0x180500
	s_addc_u32 s11, s29, 0
	s_add_u32 s12, s28, 0x180600
	s_addc_u32 s13, s29, 0
	s_add_u32 s14, s28, 0x180700
	s_addc_u32 s15, s29, 0
	s_add_u32 s16, s28, 0x180800
	s_addc_u32 s17, s29, 0
	s_add_u32 s18, s28, 0x180900
	s_addc_u32 s19, s29, 0
	s_add_u32 s20, s28, 0x180a00
	s_addc_u32 s21, s29, 0
	s_add_u32 s34, s28, 0x180b00
	s_addc_u32 s35, s29, 0
	s_add_u32 s38, s28, 0x180c00
	s_addc_u32 s39, s29, 0
	s_add_u32 s44, s28, 0x180d00
	s_addc_u32 s45, s29, 0
	s_add_u32 s46, s28, 0x180e00
	s_addc_u32 s47, s29, 0
	s_add_u32 s48, s28, 0x180f00
	s_addc_u32 s49, s29, 0
	s_add_u32 s50, s28, 0x181000
	s_addc_u32 s51, s29, 0
	s_add_u32 s52, s28, 0x181100
	s_addc_u32 s53, s29, 0
	s_add_u32 s54, s28, 0x181200
	s_addc_u32 s55, s29, 0
	s_mul_i32 s3, s23, s96
	s_add_u32 s56, s28, 0x181300
	s_mul_i32 s3, s3, s22
	s_addc_u32 s57, s29, 0
	s_mov_b32 s33, 1
	v_mov_b32_e32 v16, 0
	s_branch .LBB0_1012

; __device__ __forceinline__ void xcd_barrier(const XcdBarrier& b) {
;     asm volatile("s_waitcnt vmcnt(0)" ::: "memory");
;     __syncthreads();
;     if (threadIdx.x == 0) {
;         unsigned* bar = b.bar;
;         __builtin_amdgcn_s_waitcnt(0);
;         unsigned nloc = b.st[0], nx = b.st[1];
;         if (nloc == 0u) { xcd_barrier_complete(bar, b.x, nloc, nx); b.st[0] = nloc; b.st[1] = nx; }
.LBB0_1108:
	s_cmp_gt_i32 s31, 12
	s_cselect_b64 s[0:1], -1, 0
	s_and_b64 s[4:5], s[8:9], s[0:1]
	s_andn2_b64 vcc, exec, s[4:5]
	s_cbranch_vccnz .LBB0_1162
	s_waitcnt vmcnt(0)
	s_waitcnt vmcnt(0) lgkmcnt(0)
	s_barrier
	s_and_saveexec_b64 s[4:5], s[80:81]
	s_cbranch_execz .LBB0_1161
	buffer_inv sc1
	s_add_i32 s3, 0, 0x23fc0
	v_mov_b32_e32 v0, s3
	s_waitcnt vmcnt(0) expcnt(0) lgkmcnt(0)
	ds_read_b32 v2, v0
	s_add_i32 s3, 0, 0x23fc4
	v_mov_b32_e32 v0, s3
	ds_read_b32 v0, v0
	s_waitcnt lgkmcnt(1)
	v_cmp_ne_u32_e32 vcc, 0, v2
	s_cbranch_vccnz .LBB0_1125
	s_add_u32 s6, s28, 0x180200
	s_addc_u32 s7, s29, 0
	s_add_u32 s8, s28, 0x180400
	s_addc_u32 s9, s29, 0
	s_add_u32 s10, s28, 0x180500
	s_addc_u32 s11, s29, 0
	s_add_u32 s12, s28, 0x180600
	s_addc_u32 s13, s29, 0
	s_add_u32 s14, s28, 0x180700
	s_addc_u32 s15, s29, 0
	s_add_u32 s16, s28, 0x180800
	s_addc_u32 s17, s29, 0
	s_add_u32 s18, s28, 0x180900
	s_addc_u32 s19, s29, 0
	s_add_u32 s20, s28, 0x180a00
	s_addc_u32 s21, s29, 0
	s_add_u32 s34, s28, 0x180b00
	s_addc_u32 s35, s29, 0
	s_add_u32 s38, s28, 0x180c00
	s_addc_u32 s39, s29, 0
	s_add_u32 s44, s28, 0x180d00
	s_addc_u32 s45, s29, 0
	s_add_u32 s46, s28, 0x180e00
	s_addc_u32 s47, s29, 0
	s_add_u32 s48, s28, 0x180f00
	s_addc_u32 s49, s29, 0
	s_add_u32 s50, s28, 0x181000
	s_addc_u32 s51, s29, 0
	s_add_u32 s52, s28, 0x181100
	s_addc_u32 s53, s29, 0
	s_add_u32 s54, s28, 0x181200
	s_addc_u32 s55, s29, 0
	s_mul_i32 s3, s23, s96
	s_add_u32 s56, s28, 0x181300
	s_mul_i32 s3, s3, s22
	s_addc_u32 s57, s29, 0
	s_mov_b32 s33, 1
	v_mov_b32_e32 v16, 0
	s_branch .LBB0_1113

; __device__ __forceinline__ void xcd_barrier(const XcdBarrier& b) {
;     asm volatile("s_waitcnt vmcnt(0)" ::: "memory");
;     __syncthreads();
;     if (threadIdx.x == 0) {
;         unsigned* bar = b.bar;
;         __builtin_amdgcn_s_waitcnt(0);
;         unsigned nloc = b.st[0], nx = b.st[1];
;         if (nloc == 0u) { xcd_barrier_complete(bar, b.x, nloc, nx); b.st[0] = nloc; b.st[1] = nx; }
.LBB0_1453:
	s_cmp_gt_u32 s31, 13
	s_cselect_b64 s[0:1], -1, 0
	s_and_b64 s[0:1], s[10:11], s[0:1]
	s_andn2_b64 vcc, exec, s[0:1]
	s_cbranch_vccnz .LBB0_1507
	s_waitcnt vmcnt(0)
	s_waitcnt vmcnt(0) lgkmcnt(0)
	s_barrier
	s_and_saveexec_b64 s[0:1], s[80:81]
	s_cbranch_execz .LBB0_1506
	buffer_inv sc1
	s_add_i32 s3, 0, 0x23fc0
	v_mov_b32_e32 v0, s3
	s_waitcnt vmcnt(0) expcnt(0) lgkmcnt(0)
	ds_read_b32 v2, v0
	s_add_i32 s3, 0, 0x23fc4
	v_mov_b32_e32 v0, s3
	ds_read_b32 v0, v0
	s_waitcnt lgkmcnt(1)
	v_cmp_ne_u32_e32 vcc, 0, v2
	s_cbranch_vccnz .LBB0_1470
	s_add_u32 s4, s28, 0x180200
	s_addc_u32 s5, s29, 0
	s_add_u32 s6, s28, 0x180400
	s_addc_u32 s7, s29, 0
	s_add_u32 s8, s28, 0x180500
	s_addc_u32 s9, s29, 0
	s_add_u32 s10, s28, 0x180600
	s_addc_u32 s11, s29, 0
	s_add_u32 s12, s28, 0x180700
	s_addc_u32 s13, s29, 0
	s_add_u32 s14, s28, 0x180800
	s_addc_u32 s15, s29, 0
	s_add_u32 s16, s28, 0x180900
	s_addc_u32 s17, s29, 0
	s_add_u32 s18, s28, 0x180a00
	s_addc_u32 s19, s29, 0
	s_add_u32 s20, s28, 0x180b00
	s_addc_u32 s21, s29, 0
	s_add_u32 s34, s28, 0x180c00
	s_addc_u32 s35, s29, 0
	s_add_u32 s38, s28, 0x180d00
	s_addc_u32 s39, s29, 0
	s_add_u32 s44, s28, 0x180e00
	s_addc_u32 s45, s29, 0
	s_add_u32 s46, s28, 0x180f00
	s_addc_u32 s47, s29, 0
	s_add_u32 s48, s28, 0x181000
	s_addc_u32 s49, s29, 0
	s_add_u32 s50, s28, 0x181100
	s_addc_u32 s51, s29, 0
	s_add_u32 s52, s28, 0x181200
	s_addc_u32 s53, s29, 0
	s_mul_i32 s3, s23, s96
	s_add_u32 s54, s28, 0x181300
	s_mul_i32 s3, s3, s22
	s_addc_u32 s55, s29, 0
	s_mov_b32 s33, 1
	v_mov_b32_e32 v16, 0
	s_branch .LBB0_1458

; __device__ __forceinline__ unsigned xb_ld(unsigned* p)              { return __hip_atomic_load(p, __ATOMIC_RELAXED, __HIP_MEMORY_SCOPE_AGENT); }
; #define XB_SPIN(cond, bar) do { unsigned _sp = 0; while (cond) { __builtin_amdgcn_s_sleep(1); \
;     if ((++_sp & 255u) == 0u) { if (xb_ld(&(bar)[XB_TMO])) break; if (_sp > XB_SPIN_CAP) { atomicAdd(&(bar)[XB_TMO], 1u); break; } } } } while (0)
; __device__ __forceinline__ void xcd_barrier(const XcdBarrier& b) {
;     ...
;         } else {
;             XB_SPIN(xb_ld(&bar[XB_XGEN(b.x)]) == gen, bar);
;             __builtin_amdgcn_fence(__ATOMIC_ACQUIRE, "agent");
;             asm volatile("s_waitcnt vmcnt(0)" ::: "memory");
;         }
.LBB0_1485:
	s_or_b64 exec, exec, s[8:9]
	s_waitcnt vmcnt(0)
	s_waitcnt vmcnt(0)

; __device__ __forceinline__ unsigned xb_ld(unsigned* p)              { return __hip_atomic_load(p, __ATOMIC_RELAXED, __HIP_MEMORY_SCOPE_AGENT); }
; __device__ __forceinline__ unsigned xb_add(unsigned* p, unsigned v) { return __hip_atomic_fetch_add(p, v, __ATOMIC_RELAXED, __HIP_MEMORY_SCOPE_AGENT); }
; #define XB_SPIN(cond, bar) do { unsigned _sp = 0; while (cond) { __builtin_amdgcn_s_sleep(1); \
;     if ((++_sp & 255u) == 0u) { if (xb_ld(&(bar)[XB_TMO])) break; if (_sp > XB_SPIN_CAP) { atomicAdd(&(bar)[XB_TMO], 1u); break; } } } } while (0)
; __device__ __forceinline__ void xcd_barrier(const XcdBarrier& b) {
;     ...
;             else XB_SPIN(xb_ld(&bar[XB_TOPGEN]) == tg, bar);
;             __builtin_amdgcn_fence(__ATOMIC_ACQUIRE, "agent");
;             xb_add(&bar[XB_XGEN(b.x)], 1u);
;             asm volatile("s_waitcnt vmcnt(0)" ::: "memory");
.LBB0_1503:
	s_or_b64 exec, exec, s[6:7]
	s_mov_b64 s[6:7], exec
	v_mbcnt_lo_u32_b32 v0, s6, 0
	v_mbcnt_hi_u32_b32 v0, s7, v0
	v_cmp_eq_u32_e32 vcc, 0, v0
	s_waitcnt vmcnt(0)
	s_and_saveexec_b64 s[8:9], vcc
	s_cbranch_execz .LBB0_1505
	s_bcnt1_i32_b64 s3, s[6:7]
	v_mov_b32_e32 v0, 0x2000
	v_mov_b32_e32 v1, s3
	global_atomic_add v0, v1, s[4:5] offset:1024

; __device__ __forceinline__ void xcd_barrier(const XcdBarrier& b) {
;     asm volatile("s_waitcnt vmcnt(0)" ::: "memory");
;     __syncthreads();
;     if (threadIdx.x == 0) {
;         unsigned* bar = b.bar;
;         __builtin_amdgcn_s_waitcnt(0);
;         unsigned nloc = b.st[0], nx = b.st[1];
;         if (nloc == 0u) { xcd_barrier_complete(bar, b.x, nloc, nx); b.st[0] = nloc; b.st[1] = nx; }
.LBB0_1561:
	s_cmp_gt_i32 s31, 15
	s_cselect_b64 s[0:1], -1, 0
	s_and_b64 s[4:5], s[38:39], s[0:1]
	s_andn2_b64 vcc, exec, s[4:5]
	s_cbranch_vccnz .LBB0_1615
	s_waitcnt vmcnt(0)
	s_waitcnt vmcnt(0) lgkmcnt(0)
	s_barrier
	s_and_saveexec_b64 s[4:5], s[80:81]
	s_cbranch_execz .LBB0_1614
	buffer_inv sc1
	s_add_i32 s3, 0, 0x23fc0
	v_mov_b32_e32 v0, s3
	s_waitcnt vmcnt(0) expcnt(0) lgkmcnt(0)
	ds_read_b32 v2, v0
	s_add_i32 s3, 0, 0x23fc4
	v_mov_b32_e32 v0, s3
	ds_read_b32 v0, v0
	s_waitcnt lgkmcnt(1)
	v_cmp_ne_u32_e32 vcc, 0, v2
	s_cbranch_vccnz .LBB0_1578
	s_add_u32 s6, s28, 0x180200
	s_addc_u32 s7, s29, 0
	s_add_u32 s8, s28, 0x180400
	s_addc_u32 s9, s29, 0
	s_add_u32 s10, s28, 0x180500
	s_addc_u32 s11, s29, 0
	s_add_u32 s12, s28, 0x180600
	s_addc_u32 s13, s29, 0
	s_add_u32 s14, s28, 0x180700
	s_addc_u32 s15, s29, 0
	s_add_u32 s16, s28, 0x180800
	s_addc_u32 s17, s29, 0
	s_add_u32 s20, s28, 0x180900
	s_addc_u32 s21, s29, 0
	s_add_u32 s34, s28, 0x180a00
	s_addc_u32 s35, s29, 0
	s_add_u32 s38, s28, 0x180b00
	s_addc_u32 s39, s29, 0
	s_add_u32 s42, s28, 0x180c00
	s_addc_u32 s43, s29, 0
	s_add_u32 s44, s28, 0x180d00
	s_addc_u32 s45, s29, 0
	s_add_u32 s46, s28, 0x180e00
	s_addc_u32 s47, s29, 0
	s_add_u32 s48, s28, 0x180f00
	s_addc_u32 s49, s29, 0
	s_add_u32 s50, s28, 0x181000
	s_addc_u32 s51, s29, 0
	s_add_u32 s52, s28, 0x181100
	s_addc_u32 s53, s29, 0
	s_add_u32 s54, s28, 0x181200
	s_addc_u32 s55, s29, 0
	s_mul_i32 s3, s23, s96
	s_add_u32 s56, s28, 0x181300
	s_mul_i32 s3, s3, s22
	s_addc_u32 s57, s29, 0
	s_mov_b32 s33, 1
	v_mov_b32_e32 v16, 0
	s_branch .LBB0_1566

; __device__ __forceinline__ void xcd_barrier(const XcdBarrier& b) {
;     asm volatile("s_waitcnt vmcnt(0)" ::: "memory");
;     __syncthreads();
;     if (threadIdx.x == 0) {
;         unsigned* bar = b.bar;
;         __builtin_amdgcn_s_waitcnt(0);
;         unsigned nloc = b.st[0], nx = b.st[1];
;         if (nloc == 0u) { xcd_barrier_complete(bar, b.x, nloc, nx); b.st[0] = nloc; b.st[1] = nx; }
.LBB0_1658:
	s_cmp_gt_i32 s31, 16
	s_cselect_b64 s[4:5], -1, 0
	s_and_b64 s[0:1], s[0:1], s[4:5]
	s_andn2_b64 vcc, exec, s[0:1]
	s_cbranch_vccnz .LBB0_1712
	s_waitcnt vmcnt(0)
	s_waitcnt vmcnt(0) lgkmcnt(0)
	s_barrier
	s_and_saveexec_b64 s[0:1], s[80:81]
	s_cbranch_execz .LBB0_1711
	buffer_inv sc1
	s_add_i32 s3, 0, 0x23fc0
	v_mov_b32_e32 v0, s3
	s_waitcnt vmcnt(0) expcnt(0) lgkmcnt(0)
	ds_read_b32 v2, v0
	s_add_i32 s3, 0, 0x23fc4
	v_mov_b32_e32 v0, s3
	ds_read_b32 v0, v0
	s_waitcnt lgkmcnt(1)
	v_cmp_ne_u32_e32 vcc, 0, v2
	s_cbranch_vccnz .LBB0_1675
	s_add_u32 s6, s28, 0x180200
	s_addc_u32 s7, s29, 0
	s_add_u32 s8, s28, 0x180400
	s_addc_u32 s9, s29, 0
	s_add_u32 s10, s28, 0x180500
	s_addc_u32 s11, s29, 0
	s_add_u32 s12, s28, 0x180600
	s_addc_u32 s13, s29, 0
	s_add_u32 s14, s28, 0x180700
	s_addc_u32 s15, s29, 0
	s_add_u32 s16, s28, 0x180800
	s_addc_u32 s17, s29, 0
	s_add_u32 s18, s28, 0x180900
	s_addc_u32 s19, s29, 0
	s_add_u32 s20, s28, 0x180a00
	s_addc_u32 s21, s29, 0
	s_add_u32 s34, s28, 0x180b00
	s_addc_u32 s35, s29, 0
	s_add_u32 s38, s28, 0x180c00
	s_addc_u32 s39, s29, 0
	s_add_u32 s42, s28, 0x180d00
	s_addc_u32 s43, s29, 0
	s_add_u32 s44, s28, 0x180e00
	s_addc_u32 s45, s29, 0
	s_add_u32 s46, s28, 0x180f00
	s_addc_u32 s47, s29, 0
	s_add_u32 s48, s28, 0x181000
	s_addc_u32 s49, s29, 0
	s_add_u32 s50, s28, 0x181100
	s_addc_u32 s51, s29, 0
	s_add_u32 s52, s28, 0x181200
	s_addc_u32 s53, s29, 0
	s_mul_i32 s3, s23, s96
	s_add_u32 s54, s28, 0x181300
	s_mul_i32 s3, s3, s22
	s_addc_u32 s55, s29, 0
	s_mov_b32 s33, 1
	v_mov_b32_e32 v16, 0
	s_branch .LBB0_1663

; __device__ __forceinline__ void xcd_barrier(const XcdBarrier& b) {
;     asm volatile("s_waitcnt vmcnt(0)" ::: "memory");
;     __syncthreads();
;     if (threadIdx.x == 0) {
;         unsigned* bar = b.bar;
;         __builtin_amdgcn_s_waitcnt(0);
;         unsigned nloc = b.st[0], nx = b.st[1];
;         if (nloc == 0u) { xcd_barrier_complete(bar, b.x, nloc, nx); b.st[0] = nloc; b.st[1] = nx; }
.LBB0_1747:
	s_cmp_gt_i32 s31, 17
	s_cselect_b64 s[0:1], -1, 0
	s_and_b64 s[4:5], s[6:7], s[0:1]
	s_andn2_b64 vcc, exec, s[4:5]
	s_cbranch_vccnz .LBB0_1801
	s_waitcnt vmcnt(0)
	s_waitcnt vmcnt(0) lgkmcnt(0)
	s_barrier
	s_and_saveexec_b64 s[4:5], s[80:81]
	s_cbranch_execz .LBB0_1800
	buffer_inv sc1
	s_add_i32 s3, 0, 0x23fc0
	v_mov_b32_e32 v0, s3
	s_waitcnt vmcnt(0) expcnt(0) lgkmcnt(0)
	ds_read_b32 v2, v0
	s_add_i32 s3, 0, 0x23fc4
	v_mov_b32_e32 v0, s3
	ds_read_b32 v0, v0
	s_waitcnt lgkmcnt(1)
	v_cmp_ne_u32_e32 vcc, 0, v2
	s_cbranch_vccnz .LBB0_1764
	s_add_u32 s6, s28, 0x180200
	s_addc_u32 s7, s29, 0
	s_add_u32 s8, s28, 0x180400
	s_addc_u32 s9, s29, 0
	s_add_u32 s10, s28, 0x180500
	s_addc_u32 s11, s29, 0
	s_add_u32 s12, s28, 0x180600
	s_addc_u32 s13, s29, 0
	s_add_u32 s14, s28, 0x180700
	s_addc_u32 s15, s29, 0
	s_add_u32 s16, s28, 0x180800
	s_addc_u32 s17, s29, 0
	s_add_u32 s18, s28, 0x180900
	s_addc_u32 s19, s29, 0
	s_add_u32 s20, s28, 0x180a00
	s_addc_u32 s21, s29, 0
	s_add_u32 s34, s28, 0x180b00
	s_addc_u32 s35, s29, 0
	s_add_u32 s38, s28, 0x180c00
	s_addc_u32 s39, s29, 0
	s_add_u32 s42, s28, 0x180d00
	s_addc_u32 s43, s29, 0
	s_add_u32 s44, s28, 0x180e00
	s_addc_u32 s45, s29, 0
	s_add_u32 s46, s28, 0x180f00
	s_addc_u32 s47, s29, 0
	s_add_u32 s48, s28, 0x181000
	s_addc_u32 s49, s29, 0
	s_add_u32 s50, s28, 0x181100
	s_addc_u32 s51, s29, 0
	s_add_u32 s52, s28, 0x181200
	s_addc_u32 s53, s29, 0
	s_mul_i32 s3, s23, s96
	s_add_u32 s54, s28, 0x181300
	s_mul_i32 s3, s3, s22
	s_addc_u32 s55, s29, 0
	s_mov_b32 s33, 1
	v_mov_b32_e32 v16, 0
	s_branch .LBB0_1752

; __device__ __forceinline__ void xcd_barrier(const XcdBarrier& b) {
;     asm volatile("s_waitcnt vmcnt(0)" ::: "memory");
;     __syncthreads();
;     if (threadIdx.x == 0) {
;         unsigned* bar = b.bar;
;         __builtin_amdgcn_s_waitcnt(0);
;         unsigned nloc = b.st[0], nx = b.st[1];
;         if (nloc == 0u) { xcd_barrier_complete(bar, b.x, nloc, nx); b.st[0] = nloc; b.st[1] = nx; }
.LBB0_1848:
	s_cmp_gt_i32 s31, 18
	s_cselect_b64 s[0:1], -1, 0
	s_and_b64 s[2:3], s[8:9], s[0:1]
	s_andn2_b64 vcc, exec, s[2:3]
	s_cbranch_vccnz .LBB0_1902
	s_waitcnt vmcnt(0)
	s_waitcnt vmcnt(0) lgkmcnt(0)
	s_barrier
	s_and_saveexec_b64 s[2:3], s[80:81]
	s_cbranch_execz .LBB0_1901
	buffer_inv sc1
	s_add_i32 s4, 0, 0x23fc0
	v_mov_b32_e32 v0, s4
	s_waitcnt vmcnt(0) expcnt(0) lgkmcnt(0)
	ds_read_b32 v2, v0
	s_add_i32 s4, 0, 0x23fc4
	v_mov_b32_e32 v0, s4
	ds_read_b32 v0, v0
	s_waitcnt lgkmcnt(1)
	v_cmp_ne_u32_e32 vcc, 0, v2
	s_cbranch_vccnz .LBB0_1865
	s_add_u32 s4, s28, 0x180200
	s_addc_u32 s5, s29, 0
	s_add_u32 s6, s28, 0x180400
	s_addc_u32 s7, s29, 0
	s_add_u32 s8, s28, 0x180500
	s_addc_u32 s9, s29, 0
	s_add_u32 s10, s28, 0x180600
	s_addc_u32 s11, s29, 0
	s_add_u32 s12, s28, 0x180700
	s_addc_u32 s13, s29, 0
	s_add_u32 s14, s28, 0x180800
	s_addc_u32 s15, s29, 0
	s_add_u32 s16, s28, 0x180900
	s_addc_u32 s17, s29, 0
	s_add_u32 s18, s28, 0x180a00
	s_addc_u32 s19, s29, 0
	s_add_u32 s20, s28, 0x180b00
	s_addc_u32 s21, s29, 0
	s_add_u32 s34, s28, 0x180c00
	s_addc_u32 s35, s29, 0
	s_add_u32 s36, s28, 0x180d00
	s_addc_u32 s37, s29, 0
	s_add_u32 s38, s28, 0x180e00
	s_addc_u32 s39, s29, 0
	s_add_u32 s40, s28, 0x180f00
	s_addc_u32 s41, s29, 0
	s_add_u32 s42, s28, 0x181000
	s_addc_u32 s43, s29, 0
	s_add_u32 s44, s28, 0x181100
	s_addc_u32 s45, s29, 0
	s_add_u32 s46, s28, 0x181200
	s_addc_u32 s47, s29, 0
	s_mul_i32 s23, s23, s96
	s_add_u32 s48, s28, 0x181300
	s_mul_i32 s23, s23, s22
	s_addc_u32 s49, s29, 0
	s_mov_b32 s31, 1
	v_mov_b32_e32 v16, 0
	s_branch .LBB0_1853

; __device__ __forceinline__ unsigned xb_ld(unsigned* p)              { return __hip_atomic_load(p, __ATOMIC_RELAXED, __HIP_MEMORY_SCOPE_AGENT); }
; __device__ __forceinline__ unsigned xb_add(unsigned* p, unsigned v) { return __hip_atomic_fetch_add(p, v, __ATOMIC_RELAXED, __HIP_MEMORY_SCOPE_AGENT); }
; #define XB_SPIN(cond, bar) do { unsigned _sp = 0; while (cond) { __builtin_amdgcn_s_sleep(1); \
;     if ((++_sp & 255u) == 0u) { if (xb_ld(&(bar)[XB_TMO])) break; if (_sp > XB_SPIN_CAP) { atomicAdd(&(bar)[XB_TMO], 1u); break; } } } } while (0)
; __device__ __forceinline__ void xcd_barrier(const XcdBarrier& b) {
;     ...
;             else XB_SPIN(xb_ld(&bar[XB_TOPGEN]) == tg, bar);
;             __builtin_amdgcn_fence(__ATOMIC_ACQUIRE, "agent");
;             xb_add(&bar[XB_XGEN(b.x)], 1u);
;             asm volatile("s_waitcnt vmcnt(0)" ::: "memory");
.LBB0_1898:
	s_or_b64 exec, exec, s[6:7]
	s_mov_b64 s[6:7], exec
	v_mbcnt_lo_u32_b32 v0, s6, 0
	v_mbcnt_hi_u32_b32 v0, s7, v0
	v_cmp_eq_u32_e32 vcc, 0, v0
	s_waitcnt vmcnt(0)
	s_and_saveexec_b64 s[8:9], vcc
	s_cbranch_execz .LBB0_1900
	s_bcnt1_i32_b64 s6, s[6:7]
	v_mov_b32_e32 v0, 0x2000
	v_mov_b32_e32 v1, s6
	global_atomic_add v0, v1, s[4:5] offset:1024
